# attention loop: static s_setprio 1 for waves 4-7 inside the main loop
# speedup vs baseline: 1.0236x; 1.0003x over previous
; __device__ __forceinline__ float max3f(float a,float b,float c){float r;asm("v_max3_f32 %0, %1, %2, %3":"=v"(r):"v"(a),"v"(b),"v"(c));return r;}
; #define SB() __builtin_amdgcn_sched_barrier(0)
; #define EXP1(x) x=__builtin_amdgcn_exp2f((x)-mh_)
; template<int THRL,bool FIRST> __device__ __forceinline__ void step_main(f32x16&p0,f32x16&p1,f32x16&n0,f32x16&n1,St&S,lds_cptr kpn,lds_cptr qp,lds_cptr vp,float*wsf,int r32,int hi,float&rm){
;     ...
;   bf16x8 ka=KF(0),kb=KF(1),kc=KF(2),kd=KF(3),qa=QF(0),qb=QF(1);
;   decide<THRL,FIRST>(rm,S,wsf,r32,hi);
;   u32x4 pw0,pw1,pw2,pw3; const float mh_=S.mhat; const f32x16 z=f32x16{};
;   SB();
;   n0=MF32(ka,qa,z); ka=KF(4); EXP1(p0[0]);EXP1(p0[1]);EXP1(p0[2]); SB();
;   n1=MF32(kb,qa,z); kb=KF(5); qa=QF(2); EXP1(p0[3]);EXP1(p0[4]);EXP1(p0[5]); SB();
;   n0=MF32(kc,qb,n0);   kc=KF(6); EXP1(p0[6]);EXP1(p0[7]);EXP1(p0[8]); SB();
;   n1=MF32(kd,qb,n1);   kd=KF(7); qb=QF(3); EXP1(p0[9]);EXP1(p0[10]);EXP1(p0[11]); SB();
;   bf16x8 vfa=vfrag(vp,0);
;   n0=MF32(ka,qa,n0);   EXP1(p0[12]);EXP1(p0[13]);EXP1(p0[14]); pw0=packw(p0,0); SB();
;   bf16x8 vfb=vfrag(vp,1);
;   n1=MF32(kb,qa,n1);   EXP1(p0[15]);EXP1(p1[0]);EXP1(p1[1]); SB();
;   bf16x8 vfc=vfrag(vp,2);
;   n0=MF32(kc,qb,n0);   EXP1(p1[2]);EXP1(p1[3]);EXP1(p1[4]); pw1=packw(p0,8); SB();
;   bf16x8 vfd=vfrag(vp,3);
;   n1=MF32(kd,qb,n1);   EXP1(p1[5]);EXP1(p1[6]);EXP1(p1[7]); SB();
;     ...
;   float sa=p0[0]+p0[1];
;     ...
;   PVG(0,pw0,vfa,4, p0[2],p0[3],p0[4],p0[5],   do{EXP1(p1[8]);EXP1(p1[9]);}while(0));
;   PVG(1,pw0,vfb,5, p0[6],p0[7],p0[8],p0[9], do{EXP1(p1[10]);EXP1(p1[11]);}while(0));
;   PVG(2,pw0,vfc,6, p0[10],p0[11],p0[12],p0[13], do{EXP1(p1[12]);EXP1(p1[13]);}while(0));
;   PVG(3,pw0,vfd,7, p0[14],p0[15],p1[0],p1[1],   do{EXP1(p1[14]);EXP1(p1[15]);}while(0));
;   PVG(4,pw1,vfa,8, p1[2],p1[3],p1[4],p1[5],   pw2=packw(p1,0));
;   PVG(5,pw1,vfb,9, p1[6],p1[7],p1[8],p1[9], pw3=packw(p1,8));
;   PVG(6,pw1,vfc,10, p1[10],p1[11],p1[12],p1[13], do{}while(0));
;   PVG(7,pw1,vfd,11, p1[14],p1[15],0.f,0.f, do{}while(0));
;   float ma,mb;
;     ...
;   PVG(8,pw2,vfa,12,0.f,0.f,0.f,0.f, do{ma=max3f(n0[0],n0[1],n1[0]);mb=max3f(n0[2],n0[3],n1[1]);PINAB();}while(0));
;   PVG(9,pw2,vfb,13,0.f,0.f,0.f,0.f, do{ma=max3f(ma,n1[2],n1[3]);mb=max3f(mb,n0[4],n0[5]);PINAB();}while(0));
;   PVG(10,pw2,vfc,14,0.f,0.f,0.f,0.f, do{ma=max3f(ma,n0[6],n0[7]);mb=max3f(mb,n1[4],n1[5]);PINAB();}while(0));
.LBB0_275:
	s_waitcnt lgkmcnt(1)
	v_mfma_f32_32x32x16_bf16 v[98:113], v[218:221], v[214:217], 0
	ds_read_b128 v[178:181], v249 offset:20480
	v_sub_f32_e32 v82, v131, v247
	v_sub_f32_e32 v17, v130, v247
	v_exp_f32_e32 v190, v82
	v_sub_f32_e32 v82, v132, v247
	v_exp_f32_e32 v17, v17
	v_exp_f32_e32 v191, v82
	v_sub_f32_e32 v82, v133, v247
	v_exp_f32_e32 v192, v82
	v_sub_f32_e32 v82, v134, v247
	v_exp_f32_e32 v193, v82
	v_sub_f32_e32 v82, v135, v247
	v_exp_f32_e32 v194, v82
	v_mfma_f32_32x32x16_bf16 v[82:97], v[210:213], v[214:217], 0
	ds_read_b128 v[182:185], v249 offset:20992
	ds_read_b128 v[186:189], v248 offset:2048
	s_waitcnt lgkmcnt(3)
	v_mfma_f32_32x32x16_bf16 v[98:113], v[12:15], v[8:11], v[98:113]
	ds_read_b128 v[130:133], v249 offset:22528
	v_sub_f32_e32 v134, v136, v247
	v_exp_f32_e32 v195, v134
	v_sub_f32_e32 v134, v137, v247
	v_exp_f32_e32 v196, v134
	v_sub_f32_e32 v134, v138, v247
	v_exp_f32_e32 v197, v134
	v_mfma_f32_32x32x16_bf16 v[82:97], v[4:7], v[8:11], v[82:97]
	ds_read_b128 v[12:15], v249 offset:23040
	ds_read_b128 v[134:137], v248 offset:3072
	v_sub_f32_e32 v138, v139, v247
	v_exp_f32_e32 v198, v138
	v_sub_f32_e32 v138, v140, v247
	v_exp_f32_e32 v199, v138
	v_sub_f32_e32 v138, v141, v247
	v_exp_f32_e32 v200, v138
	s_waitcnt lgkmcnt(3)
	v_mfma_f32_32x32x16_bf16 v[98:113], v[178:181], v[186:189], v[98:113]
	ds_read_b64_tr_b16 v[4:5], v246 offset:40960
	ds_read_b64_tr_b16 v[6:7], v246 offset:41472
	v_sub_f32_e32 v8, v142, v247
	v_exp_f32_e32 v201, v8
	v_sub_f32_e32 v8, v143, v247
	v_exp_f32_e32 v202, v8
	v_sub_f32_e32 v8, v144, v247
	v_exp_f32_e32 v179, v8
	v_cvt_pk_bf16_f32 v8, v17, v190
	v_cvt_pk_bf16_f32 v9, v191, v192
	v_cvt_pk_bf16_f32 v10, v193, v194
	v_cvt_pk_bf16_f32 v11, v195, v196
	v_mfma_f32_32x32x16_bf16 v[82:97], v[182:185], v[186:189], v[82:97]
	ds_read_b64_tr_b16 v[138:139], v246 offset:45056
	ds_read_b64_tr_b16 v[140:141], v246 offset:45568
	v_sub_f32_e32 v114, v114, v247
	v_sub_f32_e32 v142, v145, v247
	v_exp_f32_e32 v181, v114
	v_sub_f32_e32 v114, v115, v247
	v_exp_f32_e32 v180, v142
	v_exp_f32_e32 v203, v114
	s_waitcnt lgkmcnt(4)
	v_mfma_f32_32x32x16_bf16 v[98:113], v[130:133], v[134:137], v[98:113]
	ds_read_b64_tr_b16 v[142:143], v246 offset:49152
	ds_read_b64_tr_b16 v[144:145], v246 offset:49664
	v_sub_f32_e32 v114, v116, v247
	v_exp_f32_e32 v182, v114
	v_sub_f32_e32 v114, v117, v247
	v_exp_f32_e32 v183, v114
	v_sub_f32_e32 v114, v118, v247
	v_exp_f32_e32 v184, v114
	v_cvt_pk_bf16_f32 v114, v197, v198
	v_cvt_pk_bf16_f32 v115, v199, v200
	v_cvt_pk_bf16_f32 v116, v201, v202
	v_cvt_pk_bf16_f32 v117, v179, v180
	v_mfma_f32_32x32x16_bf16 v[82:97], v[12:15], v[134:137], v[82:97]
	ds_read_b64_tr_b16 v[130:131], v246 offset:53248
	ds_read_b64_tr_b16 v[132:133], v246 offset:53760
	v_sub_f32_e32 v118, v119, v247
	v_exp_f32_e32 v185, v118
	v_sub_f32_e32 v118, v120, v247
	v_exp_f32_e32 v186, v118
	v_sub_f32_e32 v118, v121, v247
	v_exp_f32_e32 v187, v118
	s_waitcnt lgkmcnt(6)
	v_mfma_f32_32x32x16_bf16 v[18:33], v[8:11], v[4:7], v[18:33]
	ds_read_b64_tr_b16 v[12:13], v246 offset:41984
	ds_read_b64_tr_b16 v[14:15], v246 offset:42496
	v_sub_f32_e32 v118, v122, v247
	v_exp_f32_e32 v134, v118
	v_sub_f32_e32 v118, v123, v247
	v_exp_f32_e32 v135, v118
	s_waitcnt lgkmcnt(6)
	v_mfma_f32_32x32x16_bf16 v[34:49], v[8:11], v[138:141], v[34:49]
	ds_read_b64_tr_b16 v[4:5], v246 offset:46080
	ds_read_b64_tr_b16 v[6:7], v246 offset:46592
	v_sub_f32_e32 v118, v124, v247
	v_exp_f32_e32 v136, v118
	v_sub_f32_e32 v118, v125, v247
	v_exp_f32_e32 v137, v118
	s_waitcnt lgkmcnt(6)
	v_mfma_f32_32x32x16_bf16 v[50:65], v[8:11], v[142:145], v[50:65]
	ds_read_b64_tr_b16 v[118:119], v246 offset:50176
	ds_read_b64_tr_b16 v[120:121], v246 offset:50688
	v_sub_f32_e32 v122, v126, v247
	v_exp_f32_e32 v138, v122
	v_sub_f32_e32 v122, v127, v247
	v_exp_f32_e32 v139, v122
	s_waitcnt lgkmcnt(6)
	v_mfma_f32_32x32x16_bf16 v[66:81], v[8:11], v[130:133], v[66:81]
	ds_read_b64_tr_b16 v[122:123], v246 offset:54272
	ds_read_b64_tr_b16 v[124:125], v246 offset:54784
	v_sub_f32_e32 v126, v128, v247
	v_exp_f32_e32 v140, v126
	v_sub_f32_e32 v126, v129, v247
	v_exp_f32_e32 v141, v126
	s_waitcnt lgkmcnt(6)
	v_mfma_f32_32x32x16_bf16 v[18:33], v[114:117], v[12:15], v[18:33]
	ds_read_b64_tr_b16 v[8:9], v246 offset:43008
	ds_read_b64_tr_b16 v[10:11], v246 offset:43520
	v_cvt_pk_bf16_f32 v126, v181, v203
	v_cvt_pk_bf16_f32 v127, v182, v183
	v_cvt_pk_bf16_f32 v128, v184, v185
	v_cvt_pk_bf16_f32 v129, v186, v187
	s_waitcnt lgkmcnt(6)
	v_mfma_f32_32x32x16_bf16 v[34:49], v[114:117], v[4:7], v[34:49]
	ds_read_b64_tr_b16 v[12:13], v246 offset:47104
	ds_read_b64_tr_b16 v[14:15], v246 offset:47616
	v_cvt_pk_bf16_f32 v130, v134, v135
	v_cvt_pk_bf16_f32 v131, v136, v137
	v_cvt_pk_bf16_f32 v132, v138, v139
	v_cvt_pk_bf16_f32 v133, v140, v141
	s_waitcnt lgkmcnt(6)
	v_mfma_f32_32x32x16_bf16 v[50:65], v[114:117], v[118:121], v[50:65]
	ds_read_b64_tr_b16 v[4:5], v246 offset:51200
	ds_read_b64_tr_b16 v[6:7], v246 offset:51712
	s_waitcnt lgkmcnt(6)
	v_mfma_f32_32x32x16_bf16 v[66:81], v[114:117], v[122:125], v[66:81]
	ds_read_b64_tr_b16 v[118:119], v246 offset:55296
	ds_read_b64_tr_b16 v[120:121], v246 offset:55808
	s_waitcnt lgkmcnt(6)
	v_mfma_f32_32x32x16_bf16 v[18:33], v[126:129], v[8:11], v[18:33]
	ds_read_b64_tr_b16 v[114:115], v246 offset:44032
	ds_read_b64_tr_b16 v[116:117], v246 offset:44544
	v_max3_f32 v122, v98, v99, v82
	v_max3_f32 v123, v100, v101, v83
	s_nop 0
	s_waitcnt lgkmcnt(6)
	v_mfma_f32_32x32x16_bf16 v[34:49], v[126:129], v[12:15], v[34:49]
	ds_read_b64_tr_b16 v[8:9], v246 offset:48128
	ds_read_b64_tr_b16 v[10:11], v246 offset:48640
	v_max3_f32 v122, v122, v84, v85
	v_max3_f32 v123, v123, v102, v103
	s_nop 0
	s_waitcnt lgkmcnt(6)
; __device__ __forceinline__ float max3f(float a,float b,float c){float r;asm("v_max3_f32 %0, %1, %2, %3":"=v"(r):"v"(a),"v"(b),"v"(c));return r;}
; __device__ __forceinline__ float max2f(float a,float b){float r;asm("v_max_f32_e32 %0, %1, %2":"=v"(r):"v"(a),"v"(b));return r;}
; #define A128_WAITBAR() asm volatile("s_waitcnt vmcnt(0) lgkmcnt(0)\n\ts_barrier":::"memory")
;   #define PVG(i,PW,VF,NEXTI,X0,X1,Y0,Y1,EXTRA) do{ S.o[(i)&3]=MF32(__builtin_bit_cast(bf16x8,PW),VF,S.o[(i)&3]); if((NEXTI)<16){ VF=vfrag(vp,(NEXTI)<16?(NEXTI):0); } sa+=X0; sa+=X1; sa+=Y0; sa+=Y1; EXTRA; SB(); }while(0)
;   #define PINAB() asm volatile("":"+v"(ma),"+v"(mb))
; template<int THRL,bool FIRST> __device__ __forceinline__ void step_main(f32x16&p0,f32x16&p1,f32x16&n0,f32x16&n1,St&S,lds_cptr kpn,lds_cptr qp,lds_cptr vp,float*wsf,int r32,int hi,float&rm){
;     ...
;   PVG(8,pw2,vfa,12,0.f,0.f,0.f,0.f, do{ma=max3f(n0[0],n0[1],n1[0]);mb=max3f(n0[2],n0[3],n1[1]);PINAB();}while(0));
;   PVG(9,pw2,vfb,13,0.f,0.f,0.f,0.f, do{ma=max3f(ma,n1[2],n1[3]);mb=max3f(mb,n0[4],n0[5]);PINAB();}while(0));
;   PVG(10,pw2,vfc,14,0.f,0.f,0.f,0.f, do{ma=max3f(ma,n0[6],n0[7]);mb=max3f(mb,n1[4],n1[5]);PINAB();}while(0));
;   PVG(11,pw2,vfd,15,0.f,0.f,0.f,0.f, do{ma=max3f(ma,n1[6],n1[7]);mb=max3f(mb,n0[8],n0[9]);PINAB();}while(0));
;   PVG(12,pw3,vfa,16,0.f,0.f,0.f,0.f, do{ma=max3f(ma,n0[10],n0[11]);mb=max3f(mb,n1[8],n1[9]);PINAB();}while(0));
;   PVG(13,pw3,vfb,16,0.f,0.f,0.f,0.f, do{ma=max3f(ma,n1[10],n1[11]);mb=max3f(mb,n0[12],n0[13]);PINAB();}while(0));
;   PVG(14,pw3,vfc,16,0.f,0.f,0.f,0.f, do{ma=max3f(ma,n0[14],n0[15]);mb=max3f(mb,n1[12],n1[13]);PINAB();}while(0));
;   PVG(15,pw3,vfd,16,0.f,0.f,0.f,0.f, do{ma=max3f(ma,n1[14],n1[15]);ma=max2f(ma,mb);PINAB();}while(0));
;     ...
;   { auto rr=__builtin_amdgcn_permlane32_swap(__float_as_uint(ma),__float_as_uint(ma),false,false); rm=max2f(__uint_as_float(rr[0]),__uint_as_float(rr[1])); }
;     ...
;   S.l_reg+=sa;
; template<int THRL> __device__ __forceinline__ void unit(int qb,const bf16*Q,const bf16*K,const bf16*V,bf16*O,char*shm){
;     ...
;   if(NT>4){
;     rm=rowmax32<true>(pA0,pA1);
;     DMA_K(2,ks2); DMA_V(1,VBUF);
;     step_main<THRL,true>(pA0,pA1,pB0,pB1,S,kp0+ks1,qp,vp0,wsf,r32,hi,rm); A128_WAITBAR(); ROT();
;     DMA_K(3,ks2); DMA_V(2,0);
;     step_main<THRL,false>(pB0,pB1,pA0,pA1,S,kp0+ks1,qp,vp0+VBUF,wsf,r32,hi,rm); A128_WAITBAR(); ROT();
;     for(t=2;t<NT-4;t+=2){
	v_mfma_f32_32x32x16_bf16 v[50:65], v[126:129], v[4:7], v[50:65]
	ds_read_b64_tr_b16 v[12:13], v246 offset:52224
	ds_read_b64_tr_b16 v[14:15], v246 offset:52736
	v_max3_f32 v122, v122, v104, v105
	v_max3_f32 v123, v123, v86, v87
	s_nop 0
	s_waitcnt lgkmcnt(6)
	v_mfma_f32_32x32x16_bf16 v[66:81], v[126:129], v[118:121], v[66:81]
	ds_read_b64_tr_b16 v[4:5], v246 offset:56320
	ds_read_b64_tr_b16 v[6:7], v246 offset:56832
	v_max3_f32 v122, v122, v88, v89
	v_max3_f32 v123, v123, v106, v107
	s_nop 0
	s_waitcnt lgkmcnt(6)
	v_mfma_f32_32x32x16_bf16 v[18:33], v[130:133], v[114:117], v[18:33]
	v_max3_f32 v118, v122, v108, v109
	v_max3_f32 v119, v123, v90, v91
	s_nop 0
	s_waitcnt lgkmcnt(4)
	v_mfma_f32_32x32x16_bf16 v[34:49], v[130:133], v[8:11], v[34:49]
	v_max3_f32 v114, v118, v92, v93
	v_max3_f32 v115, v119, v110, v111
	s_nop 0
	s_waitcnt lgkmcnt(2)
	v_mfma_f32_32x32x16_bf16 v[50:65], v[130:133], v[12:15], v[50:65]
	v_max3_f32 v8, v114, v112, v113
	v_max3_f32 v9, v115, v94, v95
	s_nop 0
	s_waitcnt lgkmcnt(0)
	v_mfma_f32_32x32x16_bf16 v[66:81], v[130:133], v[4:7], v[66:81]
	v_max3_f32 v8, v8, v96, v97
	s_nop 0
	v_max_f32_e32 v8, v8, v9
	s_nop 0
	s_nop 0
	v_mov_b32_e32 v4, v8
	s_nop 1
	v_permlane32_swap_b32_e32 v8, v4
	v_max_f32_e32 v178, v8, v4
	v_add_f32_e32 v4, v17, v190
	v_add_f32_e32 v4, v191, v4
	v_add_f32_e32 v4, v192, v4
	v_add_f32_e32 v4, v193, v4
	v_add_f32_e32 v4, v194, v4
	v_add_f32_e32 v4, v195, v4
	v_add_f32_e32 v4, v196, v4
	v_add_f32_e32 v4, v197, v4
	v_add_f32_e32 v4, v198, v4
	v_add_f32_e32 v4, v199, v4
	v_add_f32_e32 v4, v200, v4
	v_add_f32_e32 v4, v201, v4
	v_add_f32_e32 v4, v202, v4
	v_add_f32_e32 v4, v179, v4
	v_add_f32_e32 v4, v180, v4
	v_add_f32_e32 v4, v181, v4
	v_add_f32_e32 v4, v203, v4
	v_add_f32_e32 v4, v182, v4
	v_add_f32_e32 v4, v183, v4
	v_add_f32_e32 v4, v184, v4
	v_add_f32_e32 v4, v185, v4
	v_add_f32_e32 v4, v186, v4
	v_add_f32_e32 v4, v187, v4
	v_add_f32_e32 v4, v134, v4
	v_add_f32_e32 v4, v135, v4
	v_add_f32_e32 v4, v136, v4
	v_add_f32_e32 v4, v137, v4
	v_add_f32_e32 v4, v138, v4
	v_add_f32_e32 v4, v139, v4
	v_add_f32_e32 v4, v140, v4
	s_waitcnt vmcnt(0) lgkmcnt(0)
	s_barrier
	v_add_f32_e32 v4, v141, v4
	v_add_f32_e32 v4, 0, v4
	s_add_i32 s89, s85, -4
	v_add_f32_e32 v251, v16, v4
	v_cmp_gt_u32_e64 s[6:7], 32, v243
	s_mov_b32 s90, 2
	v_lshl_add_u32 v16, v242, 2, s78
	s_movk_i32 s88, 0x2000
	s_mov_b32 s91, 0
	s_mov_b64 s[50:51], s[30:31]
	s_mov_b64 s[58:59], s[28:29]
	v_sub_f32_e32 v146, 0, v247
	v_sub_f32_e32 v147, 0, v247
	v_sub_f32_e32 v148, 0, v247
	v_sub_f32_e32 v149, 0, v247
	v_sub_f32_e32 v150, 0, v247
	v_sub_f32_e32 v151, 0, v247
	v_sub_f32_e32 v152, 0, v247
	v_sub_f32_e32 v153, 0, v247
	v_sub_f32_e32 v154, 0, v247
	v_sub_f32_e32 v155, 0, v247
	v_sub_f32_e32 v156, 0, v247
	v_sub_f32_e32 v157, 0, v247
	v_sub_f32_e32 v158, 0, v247
	v_sub_f32_e32 v159, 0, v247
	v_sub_f32_e32 v160, 0, v247
	v_sub_f32_e32 v161, 0, v247
	v_sub_f32_e32 v82, v82, v247
	v_sub_f32_e32 v83, v83, v247
	v_sub_f32_e32 v84, v84, v247
	v_sub_f32_e32 v85, v85, v247
	v_sub_f32_e32 v86, v86, v247
	v_sub_f32_e32 v87, v87, v247
	v_sub_f32_e32 v88, v88, v247
	v_sub_f32_e32 v89, v89, v247
	v_sub_f32_e32 v90, v90, v247
	v_sub_f32_e32 v91, v91, v247
	v_sub_f32_e32 v92, v92, v247
	v_sub_f32_e32 v93, v93, v247
	v_sub_f32_e32 v94, v94, v247
	v_sub_f32_e32 v95, v95, v247
	v_sub_f32_e32 v96, v96, v247
	v_sub_f32_e32 v97, v97, v247
	v_sub_f32_e32 v98, v98, v247
	v_sub_f32_e32 v99, v99, v247
	v_sub_f32_e32 v100, v100, v247
	v_sub_f32_e32 v101, v101, v247
	v_sub_f32_e32 v102, v102, v247
	v_sub_f32_e32 v103, v103, v247
	v_sub_f32_e32 v104, v104, v247
	v_sub_f32_e32 v105, v105, v247
	v_sub_f32_e32 v106, v106, v247
	v_sub_f32_e32 v107, v107, v247
	v_sub_f32_e32 v108, v108, v247
	v_sub_f32_e32 v109, v109, v247
	v_sub_f32_e32 v110, v110, v247
	v_sub_f32_e32 v111, v111, v247
	v_sub_f32_e32 v112, v112, v247
	v_sub_f32_e32 v113, v113, v247
	v_sub_f32_e32 v178, v178, v247
	s_cmpk_lt_u32 s86, 0x100
	s_cbranch_scc1 .Lattn_prio_c1
	s_setprio 1
; __device__ __forceinline__ int crow(int r,int hi){return (r&3)+8*(r>>2)+4*hi;}
; template<int THRL,bool FIRST> __device__ __forceinline__ void decide(float rm,St&S,float*wsf,int r32,int hi){
;   if(FIRST){ S.mhat=rm; }
;   else if(__any(rm-S.mhat>(float)THRL)){
;     const float dl=__builtin_fmaxf(rm-S.mhat,0.f); S.mhat+=dl;
;     const float f=__builtin_amdgcn_exp2f(-dl); S.l_reg*=f; if(hi==0)wsf[r32]=f;
;     asm volatile("s_waitcnt lgkmcnt(0)":::"memory");
;     #pragma unroll
;     for(int r=0;r<16;++r){ const float fr=wsf[crow(r,hi)];
;       #pragma unroll
;       for(int d=0;d<4;++d)S.o[d][r]*=fr; }
;   }
.Lattn_prio_c1:
	s_branch .LBB0_278
.LBB0_276:
	s_or_b64 exec, exec, s[60:61]
	s_waitcnt lgkmcnt(0)
	v_add_u32_e32 v108, s78, v2
	ds_read_b128 v[96:99], v108 offset:64
	ds_read_b128 v[100:103], v108 offset:96
	ds_read_b128 v[104:107], v108
	ds_read_b128 v[108:111], v108 offset:32
	v_add_f32_e32 v247, v247, v94
	v_sub_f32_e32 v146, v146, v94
	v_sub_f32_e32 v147, v147, v94
	v_sub_f32_e32 v148, v148, v94
	v_sub_f32_e32 v149, v149, v94
	v_sub_f32_e32 v150, v150, v94
	v_sub_f32_e32 v151, v151, v94
	v_sub_f32_e32 v152, v152, v94
	v_sub_f32_e32 v153, v153, v94
	v_sub_f32_e32 v154, v154, v94
	v_sub_f32_e32 v155, v155, v94
	v_sub_f32_e32 v156, v156, v94
	v_sub_f32_e32 v157, v157, v94
	v_sub_f32_e32 v158, v158, v94
	v_sub_f32_e32 v159, v159, v94
	v_sub_f32_e32 v160, v160, v94
	v_sub_f32_e32 v161, v161, v94
	v_sub_f32_e32 v114, v114, v94
	v_sub_f32_e32 v115, v115, v94
	v_sub_f32_e32 v116, v116, v94
	v_sub_f32_e32 v117, v117, v94
	v_sub_f32_e32 v118, v118, v94
	v_sub_f32_e32 v119, v119, v94
	v_sub_f32_e32 v120, v120, v94
	v_sub_f32_e32 v121, v121, v94
	v_sub_f32_e32 v122, v122, v94
	v_sub_f32_e32 v123, v123, v94
	v_sub_f32_e32 v124, v124, v94
	v_sub_f32_e32 v125, v125, v94
	v_sub_f32_e32 v126, v126, v94
	v_sub_f32_e32 v127, v127, v94
	v_sub_f32_e32 v128, v128, v94
	v_sub_f32_e32 v129, v129, v94
	v_sub_f32_e32 v130, v130, v94
	v_sub_f32_e32 v131, v131, v94
	v_sub_f32_e32 v132, v132, v94
	v_sub_f32_e32 v133, v133, v94
	v_sub_f32_e32 v134, v134, v94
	v_sub_f32_e32 v135, v135, v94
	v_sub_f32_e32 v136, v136, v94
	v_sub_f32_e32 v137, v137, v94
	v_sub_f32_e32 v138, v138, v94
	v_sub_f32_e32 v139, v139, v94
	v_sub_f32_e32 v140, v140, v94
	v_sub_f32_e32 v141, v141, v94
	v_sub_f32_e32 v142, v142, v94
	v_sub_f32_e32 v143, v143, v94
	v_sub_f32_e32 v144, v144, v94
	v_sub_f32_e32 v145, v145, v94
	v_mul_f32_e32 v17, v17, v95
	s_waitcnt lgkmcnt(2)
	v_pk_mul_f32 v[30:31], v[30:31], v[100:101]
	v_pk_mul_f32 v[26:27], v[26:27], v[96:97]
	s_waitcnt lgkmcnt(0)
	v_pk_mul_f32 v[22:23], v[22:23], v[108:109]
	v_pk_mul_f32 v[32:33], v[32:33], v[102:103]
	v_pk_mul_f32 v[28:29], v[28:29], v[98:99]
	v_pk_mul_f32 v[24:25], v[24:25], v[110:111]
	v_pk_mul_f32 v[20:21], v[20:21], v[106:107]
	v_pk_mul_f32 v[18:19], v[18:19], v[104:105]
	v_pk_mul_f32 v[46:47], v[46:47], v[100:101]
	v_pk_mul_f32 v[42:43], v[42:43], v[96:97]
	v_pk_mul_f32 v[38:39], v[38:39], v[108:109]
	v_pk_mul_f32 v[48:49], v[48:49], v[102:103]
	v_pk_mul_f32 v[44:45], v[44:45], v[98:99]
	v_pk_mul_f32 v[40:41], v[40:41], v[110:111]
	v_pk_mul_f32 v[36:37], v[36:37], v[106:107]
	v_pk_mul_f32 v[34:35], v[34:35], v[104:105]
	v_pk_mul_f32 v[62:63], v[62:63], v[100:101]
	v_pk_mul_f32 v[58:59], v[58:59], v[96:97]
	v_pk_mul_f32 v[54:55], v[54:55], v[108:109]
	v_pk_mul_f32 v[64:65], v[64:65], v[102:103]
	v_pk_mul_f32 v[60:61], v[60:61], v[98:99]
	v_pk_mul_f32 v[56:57], v[56:57], v[110:111]
	v_pk_mul_f32 v[52:53], v[52:53], v[106:107]
	v_pk_mul_f32 v[50:51], v[50:51], v[104:105]
	v_pk_mul_f32 v[78:79], v[78:79], v[100:101]
	v_pk_mul_f32 v[74:75], v[74:75], v[96:97]
	v_pk_mul_f32 v[70:71], v[70:71], v[108:109]
	v_pk_mul_f32 v[80:81], v[80:81], v[102:103]
	v_pk_mul_f32 v[76:77], v[76:77], v[98:99]
	v_pk_mul_f32 v[72:73], v[72:73], v[110:111]
	v_pk_mul_f32 v[68:69], v[68:69], v[106:107]
	v_pk_mul_f32 v[66:67], v[66:67], v[104:105]

; #define A128_WAITBAR() asm volatile("s_waitcnt vmcnt(0) lgkmcnt(0)\n\ts_barrier":::"memory")
;   #define DMA_K(t,so) glds16s((const char*)K+(size_t)(t)*(64*PIN*2),koff,(unsigned)__builtin_amdgcn_readfirstlane(kdst+(so)))
;   #define DMA_V(t,so) do{ glds16s((const char*)V+(size_t)(t)*(64*PIN*2),voff,(unsigned)__builtin_amdgcn_readfirstlane(vdst+(so))); glds16s((const char*)V+(size_t)(t)*(64*PIN*2)+128,voff,(unsigned)__builtin_amdgcn_readfirstlane(vdst+(so)+8192)); }while(0)
;   #define ROT() do{ ks1=ks2; ks2=(ks2==2*KBUF)?0:ks2+KBUF; }while(0)
; template<int THRL> __device__ __forceinline__ void unit(int qb,const bf16*Q,const bf16*K,const bf16*V,bf16*O,char*shm){
;     ...
;     for(t=2;t<NT-4;t+=2){
;       DMA_K(t+2,ks2); DMA_V(t+1,VBUF);
;       step_main<THRL,false>(pA0,pA1,pB0,pB1,S,kp0+ks1,qp,vp0,wsf,r32,hi,rm); A128_WAITBAR(); ROT();
;       DMA_K(t+3,ks2); DMA_V(t+2,0);
;       step_main<THRL,false>(pB0,pB1,pA0,pA1,S,kp0+ks1,qp,vp0+VBUF,wsf,r32,hi,rm); A128_WAITBAR(); ROT();
;     }
;   }
;     ...
;   BAND(0,pA0,pA1,pB0,pB1,0);
.LBB0_285:
	s_setprio 0
	v_add_f32_e32 v82, v82, v247
	v_add_f32_e32 v83, v83, v247
	v_add_f32_e32 v84, v84, v247
	v_add_f32_e32 v85, v85, v247
	v_add_f32_e32 v86, v86, v247
	v_add_f32_e32 v87, v87, v247
	v_add_f32_e32 v88, v88, v247
	v_add_f32_e32 v89, v89, v247
	v_add_f32_e32 v90, v90, v247
	v_add_f32_e32 v91, v91, v247
	v_add_f32_e32 v92, v92, v247
	v_add_f32_e32 v93, v93, v247
	v_add_f32_e32 v94, v94, v247
	v_add_f32_e32 v95, v95, v247
	v_add_f32_e32 v96, v96, v247
	v_add_f32_e32 v97, v97, v247
	v_add_f32_e32 v98, v98, v247
	v_add_f32_e32 v99, v99, v247
	v_add_f32_e32 v100, v100, v247
	v_add_f32_e32 v101, v101, v247
	v_add_f32_e32 v102, v102, v247
	v_add_f32_e32 v103, v103, v247
	v_add_f32_e32 v104, v104, v247
	v_add_f32_e32 v105, v105, v247
	v_add_f32_e32 v106, v106, v247
	v_add_f32_e32 v107, v107, v247
	v_add_f32_e32 v108, v108, v247
	v_add_f32_e32 v109, v109, v247
	v_add_f32_e32 v110, v110, v247
	v_add_f32_e32 v111, v111, v247
	v_add_f32_e32 v112, v112, v247
	v_add_f32_e32 v113, v113, v247
	v_add_f32_e32 v178, v178, v247
	s_branch .LBB0_287

;   #define QF(d0) LDSQ(qp+(d0)*1024)
; template<int THRL,bool FIRST> __device__ __forceinline__ void step_main(f32x16&p0,f32x16&p1,f32x16&n0,f32x16&n1,St&S,lds_cptr kpn,lds_cptr qp,lds_cptr vp,float*wsf,int r32,int hi,float&rm){
;     ...
;   bf16x8 ka=KF(0),kb=KF(1),kc=KF(2),kd=KF(3),qa=QF(0),qb=QF(1);
;   decide<THRL,FIRST>(rm,S,wsf,r32,hi);
;   u32x4 pw0,pw1,pw2,pw3; const float mh_=S.mhat; const f32x16 z=f32x16{};
;   SB();
;   n0=MF32(ka,qa,z); ka=KF(4); EXP1(p0[0]);EXP1(p0[1]);EXP1(p0[2]); SB();
;   n1=MF32(kb,qa,z); kb=KF(5); qa=QF(2); EXP1(p0[3]);EXP1(p0[4]);EXP1(p0[5]); SB();
;   n0=MF32(kc,qb,n0);   kc=KF(6); EXP1(p0[6]);EXP1(p0[7]);EXP1(p0[8]); SB();
;   n1=MF32(kd,qb,n1);   kd=KF(7); qb=QF(3); EXP1(p0[9]);EXP1(p0[10]);EXP1(p0[11]); SB();
;   bf16x8 vfa=vfrag(vp,0);
;   n0=MF32(ka,qa,n0);   EXP1(p0[12]);EXP1(p0[13]);EXP1(p0[14]); pw0=packw(p0,0); SB();
;   bf16x8 vfb=vfrag(vp,1);
;   n1=MF32(kb,qa,n1);   EXP1(p0[15]);EXP1(p1[0]);EXP1(p1[1]); SB();
;   bf16x8 vfc=vfrag(vp,2);
;   n0=MF32(kc,qb,n0);   EXP1(p1[2]);EXP1(p1[3]);EXP1(p1[4]); pw1=packw(p0,8); SB();
;   bf16x8 vfd=vfrag(vp,3);
;   n1=MF32(kd,qb,n1);   EXP1(p1[5]);EXP1(p1[6]);EXP1(p1[7]); SB();
;     ...
;   float sa=p0[0]+p0[1];
;     ...
;   PVG(0,pw0,vfa,4, p0[2],p0[3],p0[4],p0[5],   do{EXP1(p1[8]);EXP1(p1[9]);}while(0));
;   PVG(1,pw0,vfb,5, p0[6],p0[7],p0[8],p0[9], do{EXP1(p1[10]);EXP1(p1[11]);}while(0));
;   PVG(2,pw0,vfc,6, p0[10],p0[11],p0[12],p0[13], do{EXP1(p1[12]);EXP1(p1[13]);}while(0));
;   PVG(3,pw0,vfd,7, p0[14],p0[15],p1[0],p1[1],   do{EXP1(p1[14]);EXP1(p1[15]);}while(0));
;   PVG(4,pw1,vfa,8, p1[2],p1[3],p1[4],p1[5],   pw2=packw(p1,0));
;   PVG(5,pw1,vfb,9, p1[6],p1[7],p1[8],p1[9], pw3=packw(p1,8));
;   PVG(6,pw1,vfc,10, p1[10],p1[11],p1[12],p1[13], do{}while(0));
;   PVG(7,pw1,vfd,11, p1[14],p1[15],0.f,0.f, do{}while(0));
;   float ma,mb;
;     ...
;   PVG(8,pw2,vfa,12,0.f,0.f,0.f,0.f, do{ma=max3f(n0[0],n0[1],n1[0]);mb=max3f(n0[2],n0[3],n1[1]);PINAB();}while(0));
;   PVG(9,pw2,vfb,13,0.f,0.f,0.f,0.f, do{ma=max3f(ma,n1[2],n1[3]);mb=max3f(mb,n0[4],n0[5]);PINAB();}while(0));
;   PVG(10,pw2,vfc,14,0.f,0.f,0.f,0.f, do{ma=max3f(ma,n0[6],n0[7]);mb=max3f(mb,n1[4],n1[5]);PINAB();}while(0));
;   PVG(11,pw2,vfd,15,0.f,0.f,0.f,0.f, do{ma=max3f(ma,n1[6],n1[7]);mb=max3f(mb,n0[8],n0[9]);PINAB();}while(0));
;   PVG(12,pw3,vfa,16,0.f,0.f,0.f,0.f, do{ma=max3f(ma,n0[10],n0[11]);mb=max3f(mb,n1[8],n1[9]);PINAB();}while(0));
.LBB0_433:
	s_waitcnt lgkmcnt(1)
	v_mfma_f32_32x32x16_bf16 v[98:113], v[218:221], v[214:217], 0
	ds_read_b128 v[178:181], v249 offset:20480
	v_sub_f32_e32 v82, v131, v247
	v_sub_f32_e32 v17, v130, v247
	v_exp_f32_e32 v190, v82
	v_sub_f32_e32 v82, v132, v247
	v_exp_f32_e32 v17, v17
	v_exp_f32_e32 v191, v82
	v_sub_f32_e32 v82, v133, v247
	v_exp_f32_e32 v192, v82
	v_sub_f32_e32 v82, v134, v247
	v_exp_f32_e32 v193, v82
	v_sub_f32_e32 v82, v135, v247
	v_exp_f32_e32 v194, v82
	v_mfma_f32_32x32x16_bf16 v[82:97], v[210:213], v[214:217], 0
	ds_read_b128 v[182:185], v249 offset:20992
	ds_read_b128 v[186:189], v248 offset:2048
	s_waitcnt lgkmcnt(3)
	v_mfma_f32_32x32x16_bf16 v[98:113], v[12:15], v[8:11], v[98:113]
	ds_read_b128 v[130:133], v249 offset:22528
	v_sub_f32_e32 v134, v136, v247
	v_exp_f32_e32 v195, v134
	v_sub_f32_e32 v134, v137, v247
	v_exp_f32_e32 v196, v134
	v_sub_f32_e32 v134, v138, v247
	v_exp_f32_e32 v197, v134
	v_mfma_f32_32x32x16_bf16 v[82:97], v[4:7], v[8:11], v[82:97]
	ds_read_b128 v[12:15], v249 offset:23040
	ds_read_b128 v[134:137], v248 offset:3072
	v_sub_f32_e32 v138, v139, v247
	v_exp_f32_e32 v198, v138
	v_sub_f32_e32 v138, v140, v247
	v_exp_f32_e32 v199, v138
	v_sub_f32_e32 v138, v141, v247
	v_exp_f32_e32 v200, v138
	s_waitcnt lgkmcnt(3)
	v_mfma_f32_32x32x16_bf16 v[98:113], v[178:181], v[186:189], v[98:113]
	ds_read_b64_tr_b16 v[4:5], v246 offset:40960
	ds_read_b64_tr_b16 v[6:7], v246 offset:41472
	v_sub_f32_e32 v8, v142, v247
	v_exp_f32_e32 v201, v8
	v_sub_f32_e32 v8, v143, v247
	v_exp_f32_e32 v202, v8
	v_sub_f32_e32 v8, v144, v247
	v_exp_f32_e32 v179, v8
	v_cvt_pk_bf16_f32 v8, v17, v190
	v_cvt_pk_bf16_f32 v9, v191, v192
	v_cvt_pk_bf16_f32 v10, v193, v194
	v_cvt_pk_bf16_f32 v11, v195, v196
	v_mfma_f32_32x32x16_bf16 v[82:97], v[182:185], v[186:189], v[82:97]
	ds_read_b64_tr_b16 v[138:139], v246 offset:45056
	ds_read_b64_tr_b16 v[140:141], v246 offset:45568
	v_sub_f32_e32 v114, v114, v247
	v_sub_f32_e32 v142, v145, v247
	v_exp_f32_e32 v181, v114
	v_sub_f32_e32 v114, v115, v247
	v_exp_f32_e32 v180, v142
	v_exp_f32_e32 v203, v114
	s_waitcnt lgkmcnt(4)
	v_mfma_f32_32x32x16_bf16 v[98:113], v[130:133], v[134:137], v[98:113]
	ds_read_b64_tr_b16 v[142:143], v246 offset:49152
	ds_read_b64_tr_b16 v[144:145], v246 offset:49664
	v_sub_f32_e32 v114, v116, v247
	v_exp_f32_e32 v182, v114
	v_sub_f32_e32 v114, v117, v247
	v_exp_f32_e32 v183, v114
	v_sub_f32_e32 v114, v118, v247
	v_exp_f32_e32 v184, v114
	v_cvt_pk_bf16_f32 v114, v197, v198
	v_cvt_pk_bf16_f32 v115, v199, v200
	v_cvt_pk_bf16_f32 v116, v201, v202
	v_cvt_pk_bf16_f32 v117, v179, v180
	v_mfma_f32_32x32x16_bf16 v[82:97], v[12:15], v[134:137], v[82:97]
	ds_read_b64_tr_b16 v[130:131], v246 offset:53248
	ds_read_b64_tr_b16 v[132:133], v246 offset:53760
	v_sub_f32_e32 v118, v119, v247
	v_exp_f32_e32 v185, v118
	v_sub_f32_e32 v118, v120, v247
	v_exp_f32_e32 v186, v118
	v_sub_f32_e32 v118, v121, v247
	v_exp_f32_e32 v187, v118
	s_waitcnt lgkmcnt(6)
	v_mfma_f32_32x32x16_bf16 v[18:33], v[8:11], v[4:7], v[18:33]
	ds_read_b64_tr_b16 v[12:13], v246 offset:41984
	ds_read_b64_tr_b16 v[14:15], v246 offset:42496
	v_sub_f32_e32 v118, v122, v247
	v_exp_f32_e32 v134, v118
	v_sub_f32_e32 v118, v123, v247
	v_exp_f32_e32 v135, v118
	s_waitcnt lgkmcnt(6)
	v_mfma_f32_32x32x16_bf16 v[34:49], v[8:11], v[138:141], v[34:49]
	ds_read_b64_tr_b16 v[4:5], v246 offset:46080
	ds_read_b64_tr_b16 v[6:7], v246 offset:46592
	v_sub_f32_e32 v118, v124, v247
	v_exp_f32_e32 v136, v118
	v_sub_f32_e32 v118, v125, v247
	v_exp_f32_e32 v137, v118
	s_waitcnt lgkmcnt(6)
	v_mfma_f32_32x32x16_bf16 v[50:65], v[8:11], v[142:145], v[50:65]
	ds_read_b64_tr_b16 v[118:119], v246 offset:50176
	ds_read_b64_tr_b16 v[120:121], v246 offset:50688
	v_sub_f32_e32 v122, v126, v247
	v_exp_f32_e32 v138, v122
	v_sub_f32_e32 v122, v127, v247
	v_exp_f32_e32 v139, v122
	s_waitcnt lgkmcnt(6)
	v_mfma_f32_32x32x16_bf16 v[66:81], v[8:11], v[130:133], v[66:81]
	ds_read_b64_tr_b16 v[122:123], v246 offset:54272
	ds_read_b64_tr_b16 v[124:125], v246 offset:54784
	v_sub_f32_e32 v126, v128, v247
	v_exp_f32_e32 v140, v126
	v_sub_f32_e32 v126, v129, v247
	v_exp_f32_e32 v141, v126
	s_waitcnt lgkmcnt(6)
	v_mfma_f32_32x32x16_bf16 v[18:33], v[114:117], v[12:15], v[18:33]
	ds_read_b64_tr_b16 v[8:9], v246 offset:43008
	ds_read_b64_tr_b16 v[10:11], v246 offset:43520
	v_cvt_pk_bf16_f32 v126, v181, v203
	v_cvt_pk_bf16_f32 v127, v182, v183
	v_cvt_pk_bf16_f32 v128, v184, v185
	v_cvt_pk_bf16_f32 v129, v186, v187
	s_waitcnt lgkmcnt(6)
	v_mfma_f32_32x32x16_bf16 v[34:49], v[114:117], v[4:7], v[34:49]
	ds_read_b64_tr_b16 v[12:13], v246 offset:47104
	ds_read_b64_tr_b16 v[14:15], v246 offset:47616
	v_cvt_pk_bf16_f32 v130, v134, v135
	v_cvt_pk_bf16_f32 v131, v136, v137
	v_cvt_pk_bf16_f32 v132, v138, v139
	v_cvt_pk_bf16_f32 v133, v140, v141
	s_waitcnt lgkmcnt(6)
	v_mfma_f32_32x32x16_bf16 v[50:65], v[114:117], v[118:121], v[50:65]
	ds_read_b64_tr_b16 v[4:5], v246 offset:51200
	ds_read_b64_tr_b16 v[6:7], v246 offset:51712
	s_waitcnt lgkmcnt(6)
	v_mfma_f32_32x32x16_bf16 v[66:81], v[114:117], v[122:125], v[66:81]
	ds_read_b64_tr_b16 v[118:119], v246 offset:55296
	ds_read_b64_tr_b16 v[120:121], v246 offset:55808
	s_waitcnt lgkmcnt(6)
	v_mfma_f32_32x32x16_bf16 v[18:33], v[126:129], v[8:11], v[18:33]
	ds_read_b64_tr_b16 v[114:115], v246 offset:44032
	ds_read_b64_tr_b16 v[116:117], v246 offset:44544
	v_max3_f32 v122, v98, v99, v82
	v_max3_f32 v123, v100, v101, v83
	s_nop 0
	s_waitcnt lgkmcnt(6)
	v_mfma_f32_32x32x16_bf16 v[34:49], v[126:129], v[12:15], v[34:49]
	ds_read_b64_tr_b16 v[8:9], v246 offset:48128
	ds_read_b64_tr_b16 v[10:11], v246 offset:48640
	v_max3_f32 v122, v122, v84, v85
	v_max3_f32 v123, v123, v102, v103
	s_nop 0
	s_waitcnt lgkmcnt(6)
; __device__ __forceinline__ float max3f(float a,float b,float c){float r;asm("v_max3_f32 %0, %1, %2, %3":"=v"(r):"v"(a),"v"(b),"v"(c));return r;}
; __device__ __forceinline__ float max2f(float a,float b){float r;asm("v_max_f32_e32 %0, %1, %2":"=v"(r):"v"(a),"v"(b));return r;}
; #define A128_WAITBAR() asm volatile("s_waitcnt vmcnt(0) lgkmcnt(0)\n\ts_barrier":::"memory")
;   #define PVG(i,PW,VF,NEXTI,X0,X1,Y0,Y1,EXTRA) do{ S.o[(i)&3]=MF32(__builtin_bit_cast(bf16x8,PW),VF,S.o[(i)&3]); if((NEXTI)<16){ VF=vfrag(vp,(NEXTI)<16?(NEXTI):0); } sa+=X0; sa+=X1; sa+=Y0; sa+=Y1; EXTRA; SB(); }while(0)
; template<int THRL,bool FIRST> __device__ __forceinline__ void step_main(f32x16&p0,f32x16&p1,f32x16&n0,f32x16&n1,St&S,lds_cptr kpn,lds_cptr qp,lds_cptr vp,float*wsf,int r32,int hi,float&rm){
;     ...
;   PVG(8,pw2,vfa,12,0.f,0.f,0.f,0.f, do{ma=max3f(n0[0],n0[1],n1[0]);mb=max3f(n0[2],n0[3],n1[1]);PINAB();}while(0));
;   PVG(9,pw2,vfb,13,0.f,0.f,0.f,0.f, do{ma=max3f(ma,n1[2],n1[3]);mb=max3f(mb,n0[4],n0[5]);PINAB();}while(0));
;   PVG(10,pw2,vfc,14,0.f,0.f,0.f,0.f, do{ma=max3f(ma,n0[6],n0[7]);mb=max3f(mb,n1[4],n1[5]);PINAB();}while(0));
;   PVG(11,pw2,vfd,15,0.f,0.f,0.f,0.f, do{ma=max3f(ma,n1[6],n1[7]);mb=max3f(mb,n0[8],n0[9]);PINAB();}while(0));
;   PVG(12,pw3,vfa,16,0.f,0.f,0.f,0.f, do{ma=max3f(ma,n0[10],n0[11]);mb=max3f(mb,n1[8],n1[9]);PINAB();}while(0));
;   PVG(13,pw3,vfb,16,0.f,0.f,0.f,0.f, do{ma=max3f(ma,n1[10],n1[11]);mb=max3f(mb,n0[12],n0[13]);PINAB();}while(0));
;   PVG(14,pw3,vfc,16,0.f,0.f,0.f,0.f, do{ma=max3f(ma,n0[14],n0[15]);mb=max3f(mb,n1[12],n1[13]);PINAB();}while(0));
;   PVG(15,pw3,vfd,16,0.f,0.f,0.f,0.f, do{ma=max3f(ma,n1[14],n1[15]);ma=max2f(ma,mb);PINAB();}while(0));
;     ...
;   { auto rr=__builtin_amdgcn_permlane32_swap(__float_as_uint(ma),__float_as_uint(ma),false,false); rm=max2f(__uint_as_float(rr[0]),__uint_as_float(rr[1])); }
;     ...
;   S.l_reg+=sa;
; template<int THRL> __device__ __forceinline__ void unit(int qb,const bf16*Q,const bf16*K,const bf16*V,bf16*O,char*shm){
;     ...
;     step_main<THRL,true>(pA0,pA1,pB0,pB1,S,kp0+ks1,qp,vp0,wsf,r32,hi,rm); A128_WAITBAR(); ROT();
;     DMA_K(3,ks2); DMA_V(2,0);
;     step_main<THRL,false>(pB0,pB1,pA0,pA1,S,kp0+ks1,qp,vp0+VBUF,wsf,r32,hi,rm); A128_WAITBAR(); ROT();
;     for(t=2;t<NT-4;t+=2){
;       DMA_K(t+2,ks2); DMA_V(t+1,VBUF);
;       step_main<THRL,false>(pA0,pA1,pB0,pB1,S,kp0+ks1,qp,vp0,wsf,r32,hi,rm); A128_WAITBAR(); ROT();
	v_mfma_f32_32x32x16_bf16 v[50:65], v[126:129], v[4:7], v[50:65]
	ds_read_b64_tr_b16 v[12:13], v246 offset:52224
	ds_read_b64_tr_b16 v[14:15], v246 offset:52736
	v_max3_f32 v122, v122, v104, v105
	v_max3_f32 v123, v123, v86, v87
	s_nop 0
	s_waitcnt lgkmcnt(6)
	v_mfma_f32_32x32x16_bf16 v[66:81], v[126:129], v[118:121], v[66:81]
	ds_read_b64_tr_b16 v[4:5], v246 offset:56320
	ds_read_b64_tr_b16 v[6:7], v246 offset:56832
	v_max3_f32 v122, v122, v88, v89
	v_max3_f32 v123, v123, v106, v107
	s_nop 0
	s_waitcnt lgkmcnt(6)
	v_mfma_f32_32x32x16_bf16 v[18:33], v[130:133], v[114:117], v[18:33]
	v_max3_f32 v118, v122, v108, v109
	v_max3_f32 v119, v123, v90, v91
	s_nop 0
	s_waitcnt lgkmcnt(4)
	v_mfma_f32_32x32x16_bf16 v[34:49], v[130:133], v[8:11], v[34:49]
	v_max3_f32 v114, v118, v92, v93
	v_max3_f32 v115, v119, v110, v111
	s_nop 0
	s_waitcnt lgkmcnt(2)
	v_mfma_f32_32x32x16_bf16 v[50:65], v[130:133], v[12:15], v[50:65]
	v_max3_f32 v8, v114, v112, v113
	v_max3_f32 v9, v115, v94, v95
	s_nop 0
	s_waitcnt lgkmcnt(0)
	v_mfma_f32_32x32x16_bf16 v[66:81], v[130:133], v[4:7], v[66:81]
	v_max3_f32 v8, v8, v96, v97
	s_nop 0
	v_max_f32_e32 v8, v8, v9
	s_nop 0
	s_nop 0
	v_mov_b32_e32 v4, v8
	s_nop 1
	v_permlane32_swap_b32_e32 v8, v4
	v_max_f32_e32 v178, v8, v4
	v_add_f32_e32 v4, v17, v190
	v_add_f32_e32 v4, v191, v4
	v_add_f32_e32 v4, v192, v4
	v_add_f32_e32 v4, v193, v4
	v_add_f32_e32 v4, v194, v4
	v_add_f32_e32 v4, v195, v4
	v_add_f32_e32 v4, v196, v4
	v_add_f32_e32 v4, v197, v4
	v_add_f32_e32 v4, v198, v4
	v_add_f32_e32 v4, v199, v4
	v_add_f32_e32 v4, v200, v4
	v_add_f32_e32 v4, v201, v4
	v_add_f32_e32 v4, v202, v4
	v_add_f32_e32 v4, v179, v4
	v_add_f32_e32 v4, v180, v4
	v_add_f32_e32 v4, v181, v4
	v_add_f32_e32 v4, v203, v4
	v_add_f32_e32 v4, v182, v4
	v_add_f32_e32 v4, v183, v4
	v_add_f32_e32 v4, v184, v4
	v_add_f32_e32 v4, v185, v4
	v_add_f32_e32 v4, v186, v4
	v_add_f32_e32 v4, v187, v4
	v_add_f32_e32 v4, v134, v4
	v_add_f32_e32 v4, v135, v4
	v_add_f32_e32 v4, v136, v4
	v_add_f32_e32 v4, v137, v4
	v_add_f32_e32 v4, v138, v4
	v_add_f32_e32 v4, v139, v4
	v_add_f32_e32 v4, v140, v4
	s_waitcnt vmcnt(0) lgkmcnt(0)
	s_barrier
	v_add_f32_e32 v4, v141, v4
	v_add_f32_e32 v4, 0, v4
	s_add_i32 s87, s83, -4
	v_add_f32_e32 v251, v16, v4
	v_cmp_gt_u32_e64 s[6:7], 32, v243
	s_mov_b32 s88, 2
	v_lshl_add_u32 v16, v242, 2, s76
	s_movk_i32 s86, 0x2000
	s_mov_b32 s89, 0
	s_mov_b64 s[48:49], s[34:35]
	s_mov_b64 s[50:51], s[30:31]
	v_sub_f32_e32 v146, 0, v247
	v_sub_f32_e32 v147, 0, v247
	v_sub_f32_e32 v148, 0, v247
	v_sub_f32_e32 v149, 0, v247
	v_sub_f32_e32 v150, 0, v247
	v_sub_f32_e32 v151, 0, v247
	v_sub_f32_e32 v152, 0, v247
	v_sub_f32_e32 v153, 0, v247
	v_sub_f32_e32 v154, 0, v247
	v_sub_f32_e32 v155, 0, v247
	v_sub_f32_e32 v156, 0, v247
	v_sub_f32_e32 v157, 0, v247
	v_sub_f32_e32 v158, 0, v247
	v_sub_f32_e32 v159, 0, v247
	v_sub_f32_e32 v160, 0, v247
	v_sub_f32_e32 v161, 0, v247
	v_sub_f32_e32 v82, v82, v247
	v_sub_f32_e32 v83, v83, v247
	v_sub_f32_e32 v84, v84, v247
	v_sub_f32_e32 v85, v85, v247
	v_sub_f32_e32 v86, v86, v247
	v_sub_f32_e32 v87, v87, v247
	v_sub_f32_e32 v88, v88, v247
	v_sub_f32_e32 v89, v89, v247
	v_sub_f32_e32 v90, v90, v247
	v_sub_f32_e32 v91, v91, v247
	v_sub_f32_e32 v92, v92, v247
	v_sub_f32_e32 v93, v93, v247
	v_sub_f32_e32 v94, v94, v247
	v_sub_f32_e32 v95, v95, v247
	v_sub_f32_e32 v96, v96, v247
	v_sub_f32_e32 v97, v97, v247
	v_sub_f32_e32 v98, v98, v247
	v_sub_f32_e32 v99, v99, v247
	v_sub_f32_e32 v100, v100, v247
	v_sub_f32_e32 v101, v101, v247
	v_sub_f32_e32 v102, v102, v247
	v_sub_f32_e32 v103, v103, v247
	v_sub_f32_e32 v104, v104, v247
	v_sub_f32_e32 v105, v105, v247
	v_sub_f32_e32 v106, v106, v247
	v_sub_f32_e32 v107, v107, v247
	v_sub_f32_e32 v108, v108, v247
	v_sub_f32_e32 v109, v109, v247
	v_sub_f32_e32 v110, v110, v247
	v_sub_f32_e32 v111, v111, v247
	v_sub_f32_e32 v112, v112, v247
	v_sub_f32_e32 v113, v113, v247
	v_sub_f32_e32 v178, v178, v247
	s_cmpk_lt_u32 s84, 0x100
	s_cbranch_scc1 .Lattn_prio_c2
	s_setprio 1
; __device__ __forceinline__ int crow(int r,int hi){return (r&3)+8*(r>>2)+4*hi;}
; template<int THRL,bool FIRST> __device__ __forceinline__ void decide(float rm,St&S,float*wsf,int r32,int hi){
;   if(FIRST){ S.mhat=rm; }
;   else if(__any(rm-S.mhat>(float)THRL)){
;     const float dl=__builtin_fmaxf(rm-S.mhat,0.f); S.mhat+=dl;
;     const float f=__builtin_amdgcn_exp2f(-dl); S.l_reg*=f; if(hi==0)wsf[r32]=f;
;     asm volatile("s_waitcnt lgkmcnt(0)":::"memory");
;     #pragma unroll
;     for(int r=0;r<16;++r){ const float fr=wsf[crow(r,hi)];
;       #pragma unroll
;       for(int d=0;d<4;++d)S.o[d][r]*=fr; }
;   }
.Lattn_prio_c2:
	s_branch .LBB0_436
.LBB0_434:
	s_or_b64 exec, exec, s[58:59]
	s_waitcnt lgkmcnt(0)
	v_add_u32_e32 v108, s76, v2
	ds_read_b128 v[96:99], v108 offset:64
	ds_read_b128 v[100:103], v108 offset:96
	ds_read_b128 v[104:107], v108
	ds_read_b128 v[108:111], v108 offset:32
	v_add_f32_e32 v247, v247, v94
	v_sub_f32_e32 v146, v146, v94
	v_sub_f32_e32 v147, v147, v94
	v_sub_f32_e32 v148, v148, v94
	v_sub_f32_e32 v149, v149, v94
	v_sub_f32_e32 v150, v150, v94
	v_sub_f32_e32 v151, v151, v94
	v_sub_f32_e32 v152, v152, v94
	v_sub_f32_e32 v153, v153, v94
	v_sub_f32_e32 v154, v154, v94
	v_sub_f32_e32 v155, v155, v94
	v_sub_f32_e32 v156, v156, v94
	v_sub_f32_e32 v157, v157, v94
	v_sub_f32_e32 v158, v158, v94
	v_sub_f32_e32 v159, v159, v94
	v_sub_f32_e32 v160, v160, v94
	v_sub_f32_e32 v161, v161, v94
	v_sub_f32_e32 v114, v114, v94
	v_sub_f32_e32 v115, v115, v94
	v_sub_f32_e32 v116, v116, v94
	v_sub_f32_e32 v117, v117, v94
	v_sub_f32_e32 v118, v118, v94
	v_sub_f32_e32 v119, v119, v94
	v_sub_f32_e32 v120, v120, v94
	v_sub_f32_e32 v121, v121, v94
	v_sub_f32_e32 v122, v122, v94
	v_sub_f32_e32 v123, v123, v94
	v_sub_f32_e32 v124, v124, v94
	v_sub_f32_e32 v125, v125, v94
	v_sub_f32_e32 v126, v126, v94
	v_sub_f32_e32 v127, v127, v94
	v_sub_f32_e32 v128, v128, v94
	v_sub_f32_e32 v129, v129, v94
	v_sub_f32_e32 v130, v130, v94
	v_sub_f32_e32 v131, v131, v94
	v_sub_f32_e32 v132, v132, v94
	v_sub_f32_e32 v133, v133, v94
	v_sub_f32_e32 v134, v134, v94
	v_sub_f32_e32 v135, v135, v94
	v_sub_f32_e32 v136, v136, v94
	v_sub_f32_e32 v137, v137, v94
	v_sub_f32_e32 v138, v138, v94
	v_sub_f32_e32 v139, v139, v94
	v_sub_f32_e32 v140, v140, v94
	v_sub_f32_e32 v141, v141, v94
	v_sub_f32_e32 v142, v142, v94
	v_sub_f32_e32 v143, v143, v94
	v_sub_f32_e32 v144, v144, v94
	v_sub_f32_e32 v145, v145, v94
	v_mul_f32_e32 v17, v17, v95
	s_waitcnt lgkmcnt(2)
	v_pk_mul_f32 v[30:31], v[30:31], v[100:101]
	v_pk_mul_f32 v[26:27], v[26:27], v[96:97]
	s_waitcnt lgkmcnt(0)
	v_pk_mul_f32 v[22:23], v[22:23], v[108:109]
	v_pk_mul_f32 v[32:33], v[32:33], v[102:103]
	v_pk_mul_f32 v[28:29], v[28:29], v[98:99]
	v_pk_mul_f32 v[24:25], v[24:25], v[110:111]
	v_pk_mul_f32 v[20:21], v[20:21], v[106:107]
	v_pk_mul_f32 v[18:19], v[18:19], v[104:105]
	v_pk_mul_f32 v[46:47], v[46:47], v[100:101]
	v_pk_mul_f32 v[42:43], v[42:43], v[96:97]
	v_pk_mul_f32 v[38:39], v[38:39], v[108:109]
	v_pk_mul_f32 v[48:49], v[48:49], v[102:103]
	v_pk_mul_f32 v[44:45], v[44:45], v[98:99]
	v_pk_mul_f32 v[40:41], v[40:41], v[110:111]
	v_pk_mul_f32 v[36:37], v[36:37], v[106:107]
	v_pk_mul_f32 v[34:35], v[34:35], v[104:105]
	v_pk_mul_f32 v[62:63], v[62:63], v[100:101]
	v_pk_mul_f32 v[58:59], v[58:59], v[96:97]
	v_pk_mul_f32 v[54:55], v[54:55], v[108:109]
	v_pk_mul_f32 v[64:65], v[64:65], v[102:103]
	v_pk_mul_f32 v[60:61], v[60:61], v[98:99]
	v_pk_mul_f32 v[56:57], v[56:57], v[110:111]
	v_pk_mul_f32 v[52:53], v[52:53], v[106:107]
	v_pk_mul_f32 v[50:51], v[50:51], v[104:105]
	v_pk_mul_f32 v[78:79], v[78:79], v[100:101]
	v_pk_mul_f32 v[74:75], v[74:75], v[96:97]
	v_pk_mul_f32 v[70:71], v[70:71], v[108:109]
	v_pk_mul_f32 v[80:81], v[80:81], v[102:103]
	v_pk_mul_f32 v[76:77], v[76:77], v[98:99]
	v_pk_mul_f32 v[72:73], v[72:73], v[110:111]
	v_pk_mul_f32 v[68:69], v[68:69], v[106:107]
	v_pk_mul_f32 v[66:67], v[66:67], v[104:105]

; __device__ __forceinline__ int crow(int r,int hi){return (r&3)+8*(r>>2)+4*hi;}
; template<int THRL,bool FIRST> __device__ __forceinline__ void decide(float rm,St&S,float*wsf,int r32,int hi){
;   if(FIRST){ S.mhat=rm; }
;   else if(__any(rm-S.mhat>(float)THRL)){
;     const float dl=__builtin_fmaxf(rm-S.mhat,0.f); S.mhat+=dl;
;     const float f=__builtin_amdgcn_exp2f(-dl); S.l_reg*=f; if(hi==0)wsf[r32]=f;
;     asm volatile("s_waitcnt lgkmcnt(0)":::"memory");
;     #pragma unroll
;     for(int r=0;r<16;++r){ const float fr=wsf[crow(r,hi)];
;       #pragma unroll
;       for(int d=0;d<4;++d)S.o[d][r]*=fr; }
;   }
.Lattn_prio_c3:
	s_branch .LBB0_519
.LBB0_517:
	s_or_b64 exec, exec, s[58:59]
	s_waitcnt lgkmcnt(0)
	v_add_u32_e32 v108, s76, v2
	ds_read_b128 v[96:99], v108 offset:64
	ds_read_b128 v[100:103], v108 offset:96
	ds_read_b128 v[104:107], v108
	ds_read_b128 v[108:111], v108 offset:32
	v_add_f32_e32 v247, v247, v94
	v_sub_f32_e32 v146, v146, v94
	v_sub_f32_e32 v147, v147, v94
	v_sub_f32_e32 v148, v148, v94
	v_sub_f32_e32 v149, v149, v94
	v_sub_f32_e32 v150, v150, v94
	v_sub_f32_e32 v151, v151, v94
	v_sub_f32_e32 v152, v152, v94
	v_sub_f32_e32 v153, v153, v94
	v_sub_f32_e32 v154, v154, v94
	v_sub_f32_e32 v155, v155, v94
	v_sub_f32_e32 v156, v156, v94
	v_sub_f32_e32 v157, v157, v94
	v_sub_f32_e32 v158, v158, v94
	v_sub_f32_e32 v159, v159, v94
	v_sub_f32_e32 v160, v160, v94
	v_sub_f32_e32 v161, v161, v94
	v_sub_f32_e32 v114, v114, v94
	v_sub_f32_e32 v115, v115, v94
	v_sub_f32_e32 v116, v116, v94
	v_sub_f32_e32 v117, v117, v94
	v_sub_f32_e32 v118, v118, v94
	v_sub_f32_e32 v119, v119, v94
	v_sub_f32_e32 v120, v120, v94
	v_sub_f32_e32 v121, v121, v94
	v_sub_f32_e32 v122, v122, v94
	v_sub_f32_e32 v123, v123, v94
	v_sub_f32_e32 v124, v124, v94
	v_sub_f32_e32 v125, v125, v94
	v_sub_f32_e32 v126, v126, v94
	v_sub_f32_e32 v127, v127, v94
	v_sub_f32_e32 v128, v128, v94
	v_sub_f32_e32 v129, v129, v94
	v_sub_f32_e32 v130, v130, v94
	v_sub_f32_e32 v131, v131, v94
	v_sub_f32_e32 v132, v132, v94
	v_sub_f32_e32 v133, v133, v94
	v_sub_f32_e32 v134, v134, v94
	v_sub_f32_e32 v135, v135, v94
	v_sub_f32_e32 v136, v136, v94
	v_sub_f32_e32 v137, v137, v94
	v_sub_f32_e32 v138, v138, v94
	v_sub_f32_e32 v139, v139, v94
	v_sub_f32_e32 v140, v140, v94
	v_sub_f32_e32 v141, v141, v94
	v_sub_f32_e32 v142, v142, v94
	v_sub_f32_e32 v143, v143, v94
	v_sub_f32_e32 v144, v144, v94
	v_sub_f32_e32 v145, v145, v94
	v_mul_f32_e32 v17, v17, v95
	s_waitcnt lgkmcnt(2)
	v_pk_mul_f32 v[30:31], v[30:31], v[100:101]
	v_pk_mul_f32 v[26:27], v[26:27], v[96:97]
	s_waitcnt lgkmcnt(0)
	v_pk_mul_f32 v[22:23], v[22:23], v[108:109]
	v_pk_mul_f32 v[32:33], v[32:33], v[102:103]
	v_pk_mul_f32 v[28:29], v[28:29], v[98:99]
	v_pk_mul_f32 v[24:25], v[24:25], v[110:111]
	v_pk_mul_f32 v[20:21], v[20:21], v[106:107]
	v_pk_mul_f32 v[18:19], v[18:19], v[104:105]
	v_pk_mul_f32 v[46:47], v[46:47], v[100:101]
	v_pk_mul_f32 v[42:43], v[42:43], v[96:97]
	v_pk_mul_f32 v[38:39], v[38:39], v[108:109]
	v_pk_mul_f32 v[48:49], v[48:49], v[102:103]
	v_pk_mul_f32 v[44:45], v[44:45], v[98:99]
	v_pk_mul_f32 v[40:41], v[40:41], v[110:111]
	v_pk_mul_f32 v[36:37], v[36:37], v[106:107]
	v_pk_mul_f32 v[34:35], v[34:35], v[104:105]
	v_pk_mul_f32 v[62:63], v[62:63], v[100:101]
	v_pk_mul_f32 v[58:59], v[58:59], v[96:97]
	v_pk_mul_f32 v[54:55], v[54:55], v[108:109]
	v_pk_mul_f32 v[64:65], v[64:65], v[102:103]
	v_pk_mul_f32 v[60:61], v[60:61], v[98:99]
	v_pk_mul_f32 v[56:57], v[56:57], v[110:111]
	v_pk_mul_f32 v[52:53], v[52:53], v[106:107]
	v_pk_mul_f32 v[50:51], v[50:51], v[104:105]
	v_pk_mul_f32 v[78:79], v[78:79], v[100:101]
	v_pk_mul_f32 v[74:75], v[74:75], v[96:97]
	v_pk_mul_f32 v[70:71], v[70:71], v[108:109]
	v_pk_mul_f32 v[80:81], v[80:81], v[102:103]
	v_pk_mul_f32 v[76:77], v[76:77], v[98:99]
	v_pk_mul_f32 v[72:73], v[72:73], v[110:111]
	v_pk_mul_f32 v[68:69], v[68:69], v[106:107]
	v_pk_mul_f32 v[66:67], v[66:67], v[104:105]
